# late weight transposes (second half of layer-1 FFN-in, both FFN-out) deferred from P0 to the idle workgroups at the end of P1
# baseline (speedup 1.0000x reference)
.LBB0_17:
	s_or_b64 exec, exec, s[4:5]
	s_cmp_lt_i32 s40, 1
	s_cselect_b64 s[4:5], -1, 0
	s_cmp_gt_i32 s41, 0
	v_writelane_b32 v255, s34, 2
	s_cselect_b64 s[6:7], -1, 0
	s_and_b64 s[4:5], s[4:5], s[6:7]
	v_writelane_b32 v255, s35, 3
	v_writelane_b32 v255, s42, 4
	s_andn2_b64 vcc, exec, s[4:5]
	s_nop 0
	v_writelane_b32 v255, s43, 5
	s_cbranch_vccnz .LBB0_219
	s_movk_i32 s98, 7359
	s_mov_b32 s99, 0
.Lp0_items_entry:
	v_mov_b32_e32 v1, v254
	s_waitcnt lgkmcnt(0)
	s_cmp_eq_u32 s99, 0
	s_cselect_b32 s100, s2, s100
	s_cselect_b32 s101, s33, s101
	s_lshl_b32 s5, s100, 3
	v_readfirstlane_b32 s4, v1
	s_ashr_i32 s4, s4, 6
	s_lshl_b32 s26, s101, 3
	s_lshl_b32 s3, s101, 4
	v_and_b32_e32 v86, 63, v1
	s_add_i32 s6, s4, s5
	s_cmp_gt_i32 s6, s98
	v_lshlrev_b32_e32 v70, 3, v86
	s_cbranch_scc1 .Lp0_items_done
	s_lshl_b32 s5, s4, 14
	v_lshrrev_b32_e32 v28, 3, v86
	v_and_b32_e32 v2, 56, v70
	s_add_i32 s5, s5, 0
	v_lshrrev_b32_e32 v3, 5, v86
	v_mul_u32_u24_e32 v4, 0x84, v2
	v_lshlrev_b32_e32 v5, 2, v28
	s_movk_i32 s7, 0x84
	v_add3_u32 v29, s5, v4, v5
	v_or_b32_e32 v33, 2, v3
	v_mov_b32_e32 v4, 0x108
	v_mov_b32_e32 v5, 0x738
	v_mov_b32_e32 v6, 0xd68
	v_mad_u32_u24 v36, v33, s7, v4
	v_mov_b32_e32 v4, 0x318
	v_mad_u32_u24 v45, v33, s7, v5
	v_mov_b32_e32 v5, 0x948
	v_mad_u32_u24 v54, v33, s7, v6
	v_mov_b32_e32 v6, 0xf78
	v_mov_b32_e32 v7, 0x1398
	v_and_b32_e32 v0, 31, v1
	v_mad_u32_u24 v39, v33, s7, v4
	v_mov_b32_e32 v4, 0x528
	v_mad_u32_u24 v48, v33, s7, v5
	v_mov_b32_e32 v5, 0xb58
	v_mad_u32_u24 v57, v33, s7, v6
	v_mov_b32_e32 v6, 0x1188
	v_mad_u32_u24 v63, v33, s7, v7
	v_mov_b32_e32 v7, 0x15a8
	v_lshl_add_u32 v26, v0, 2, s5
	v_mad_u32_u24 v42, v33, s7, v4
	v_mov_b32_e32 v4, 0x630
	v_mad_u32_u24 v51, v33, s7, v5
	v_mov_b32_e32 v5, 0xc60
	v_mad_u32_u24 v60, v33, s7, v6
	v_mov_b32_e32 v6, 0x1290
	v_mad_u32_u24 v66, v33, s7, v7
	v_mov_b32_e32 v7, 0x17b8
	v_mad_u32_u24 v27, v3, s7, v26
	v_mad_u32_u24 v4, v33, s7, v4
	v_mad_u32_u24 v5, v33, s7, v5
	v_mad_u32_u24 v6, v33, s7, v6
	v_mad_u32_u24 v69, v33, s7, v7
	s_lshl_b32 s5, s100, 4
	s_lshl_b32 s7, s4, 1
	s_add_i32 s7, s5, s7
	s_lshl_b32 s5, s100, 8
	s_lshl_b32 s8, s4, 5
	s_add_i32 s27, s5, s8
	s_lshl_b32 s5, s100, 5
	s_lshl_b32 s8, s4, 2
	s_add_i32 s29, s5, s8
	s_lshl_b32 s5, s100, 7
	s_lshl_b32 s4, s4, 4
	s_mov_b32 s9, 0
	v_or_b32_e32 v30, 8, v28
	v_or_b32_e32 v31, 16, v28
	v_or_b32_e32 v32, 24, v28
	v_mul_u32_u24_e32 v34, 0x84, v33
	v_or_b32_e32 v35, 4, v3
	v_or_b32_e32 v37, 6, v3
	v_or_b32_e32 v38, 8, v3
	v_or_b32_e32 v40, 10, v3
	v_or_b32_e32 v41, 12, v3
	v_or_b32_e32 v43, 14, v3
	v_or_b32_e32 v44, 16, v3
	v_or_b32_e32 v46, 18, v3
	v_or_b32_e32 v47, 20, v3
	v_or_b32_e32 v49, 22, v3
	v_or_b32_e32 v50, 24, v3
	v_or_b32_e32 v52, 26, v3
	v_or_b32_e32 v53, 28, v3
	v_or_b32_e32 v55, 30, v3
	v_or_b32_e32 v56, 32, v3
	v_or_b32_e32 v58, 34, v3
	v_or_b32_e32 v59, 36, v3
	v_or_b32_e32 v61, 38, v3
	v_or_b32_e32 v62, 40, v3
	v_or_b32_e32 v64, 42, v3
	v_or_b32_e32 v65, 44, v3
	v_or_b32_e32 v67, 46, v3
	v_or_b32_e32 v68, 48, v3
	v_or_b32_e32 v71, 50, v3
	v_or_b32_e32 v72, 52, v3
	v_or_b32_e32 v73, 54, v3
	v_or_b32_e32 v74, 56, v3
	s_lshl_b32 s28, s101, 8
	s_lshl_b32 s30, s101, 5
	s_add_i32 s31, s5, s4
	s_lshl_b32 s34, s101, 7
	s_movk_i32 s35, 0x2000
	s_movk_i32 s36, 0x4000
	s_movk_i32 s37, 0x6000
	s_mov_b32 s74, 0x8000
	s_mov_b32 s39, 0xa000
	s_mov_b32 s40, 0xc000
	s_mov_b32 s41, 0xe000
	s_mov_b32 s42, 0x10000
	s_mov_b32 s43, 0x12000
	s_mov_b32 s44, 0x14000
	s_mov_b32 s45, 0x16000
	s_mov_b32 s46, 0x18000
	s_mov_b32 s47, 0x1a000
	s_mov_b32 s48, 0x1c000
	s_mov_b32 s49, 0x1e000
	s_mov_b32 s50, 0x20000
	s_mov_b32 s51, 0x22000
	s_mov_b32 s52, 0x24000
	s_mov_b32 s53, 0x26000
	s_mov_b32 s54, 0x28000
	s_mov_b32 s55, 0x2a000
	s_mov_b32 s56, 0x2c000
	s_mov_b32 s57, 0x2e000
	s_mov_b32 s58, 0x30000
	s_mov_b32 s59, 0x32000
	s_mov_b32 s60, 0x34000
	s_mov_b32 s61, 0x36000
	s_mov_b32 s62, 0x38000
	s_mov_b32 s63, 0x3a000
	s_mov_b32 s64, 0x3c000
	s_mov_b32 s65, 0x3e000
	s_movk_i32 s66, 0x5800
	v_add_u32_e32 v75, v26, v4
	v_add_u32_e32 v76, v26, v5
	v_add_u32_e32 v77, v26, v6
	s_mov_b64 s[10:11], 0x6e0000
	s_movk_i32 s67, 0x3000
	s_movk_i32 s68, 0x5000
	s_movk_i32 s69, 0x7000
	s_mov_b64 s[12:13], 0x680000
	s_movk_i32 s70, 0x1c00
	s_mov_b32 s71, 0x11000
	s_mov_b32 s80, 0x15000
	s_mov_b32 s81, 0x1f000
	s_mov_b32 s82, 0x23000
	s_mov_b32 s83, 0x2d000
	s_mov_b32 s84, 0x31000
	s_mov_b32 s85, 0x3b000
	s_mov_b32 s86, 0x3f000
	s_mov_b32 s87, 0x42000
	s_mov_b32 s88, 0x46000
	s_mov_b32 s89, 0x49000
	s_mov_b32 s90, 0x4d000
	s_mov_b32 s91, 0x50000
	s_mov_b32 s92, 0x54000
	s_mov_b32 s93, 0x57000
	s_mov_b32 s94, 0x5b000
	v_or_b32_e32 v78, 58, v3
	s_mov_b32 s95, 0x5e000
	v_or_b32_e32 v79, 60, v3
	s_mov_b32 s96, 0x62000
	v_or_b32_e32 v80, 62, v3
	s_mov_b32 s97, 0x65000
	v_mov_b32_e32 v5, 0
	s_mov_b64 s[14:15], 0x300000
	s_mov_b32 s38, s6
	s_mov_b64 s[16:17], 0x100000
	s_branch .LBB0_21
.LBB0_20:
	s_add_i32 s38, s38, s26
	s_add_i32 s7, s7, s3
	s_add_i32 s27, s27, s28
	s_add_i32 s29, s29, s30
	s_add_i32 s31, s31, s34
	s_cmp_gt_i32 s38, s98
	s_cbranch_scc1 .Lp0_items_done

.Lp0_items_done:
	s_cmp_lg_u32 s99, 0
	s_cbranch_scc1 .Lp1_items_ret

.LBB0_422:
	s_load_dwordx4 s[40:43], s[0:1], 0xc8
	s_waitcnt vmcnt(0)
	v_readlane_b32 s34, v255, 2
	s_waitcnt lgkmcnt(0)
	v_readlane_b32 s42, v255, 4
	v_readlane_b32 s35, v255, 3
	v_readlane_b32 s43, v255, 5
	s_barrier
	s_cmpk_lt_u32 s2, 0xa0
	s_cbranch_scc1 .Lp1_items_skip
	s_mov_b32 s99, 1
	s_movk_i32 s98, 0x2ddf
	s_add_i32 s100, s2, 760
	s_movk_i32 s101, 0x60
	s_branch .Lp0_items_entry
.Lp1_items_ret:
	s_mov_b32 s99, 0
	s_load_dwordx4 s[40:43], s[0:1], 0xc8
	v_readlane_b32 s34, v255, 2
	s_waitcnt lgkmcnt(0)
	v_readlane_b32 s42, v255, 4
	v_readlane_b32 s35, v255, 3
	v_readlane_b32 s43, v255, 5
.Lp1_items_skip:
.LBB0_423:
	s_cmp_lt_i32 s40, 3
	s_cselect_b64 s[4:5], -1, 0
	s_and_b64 s[8:9], s[42:43], s[4:5]
	s_cmp_gt_i32 s41, 2
	s_cselect_b64 s[6:7], -1, 0
	s_and_b64 s[8:9], s[8:9], s[6:7]
	s_andn2_b64 vcc, exec, s[8:9]
	s_cbranch_vccnz .LBB0_477
	s_waitcnt vmcnt(0)
	v_mov_b32_e32 v0, s1
	v_mov_b32_e32 v1, s0
	s_waitcnt vmcnt(0)
	s_waitcnt lgkmcnt(0)
	v_readfirstlane_b32 s10, v1
	v_readfirstlane_b32 s11, v0
	s_barrier
	s_and_saveexec_b64 s[8:9], s[34:35]
	s_cbranch_execz .LBB0_476
	s_add_i32 s12, 0, 0x23fc0
	v_mov_b32_e32 v0, s12
	s_load_dwordx2 s[10:11], s[10:11], 0xc0
	s_waitcnt vmcnt(0) expcnt(0) lgkmcnt(0)
	s_getreg_b32 s3, hwreg(HW_REG_XCC_ID, 0, 4)
	ds_read_b32 v2, v0
	s_add_i32 s12, 0, 0x23fc4
	v_mov_b32_e32 v0, s12
	ds_read_b32 v0, v0
	s_and_b32 s3, s3, 15
	s_waitcnt lgkmcnt(1)
	v_cmp_ne_u32_e32 vcc, 0, v2
	s_cbranch_vccnz .LBB0_440
	v_readlane_b32 s12, v255, 0
	v_readlane_b32 s13, v255, 1
	s_load_dwordx2 s[16:17], s[12:13], 0x4
	s_add_u32 s12, s10, 0x1000
	s_addc_u32 s13, s11, 0
	s_add_u32 s14, s10, 0x1100
	s_addc_u32 s15, s11, 0
	s_waitcnt lgkmcnt(0)
	s_mul_i32 s26, s16, s33
	s_add_u32 s16, s10, 0x1200
	s_mul_i32 s26, s26, s17
	s_addc_u32 s17, s11, 0
	s_add_u32 s18, s10, 0x1300
	s_addc_u32 s19, s11, 0
	s_mov_b32 s27, 1
	v_mov_b32_e32 v16, 0
	s_branch .LBB0_428
